# grid-barrier poll interval s_sleep 2 (was 4) now that the working blocks hold priority over the pollers
# speedup vs baseline: 1.0072x; 1.0072x over previous
.LBB0_100:
	s_sleep 2
	global_load_dword v16, v17, s[34:35] sc1
	s_waitcnt vmcnt(0)
	v_cmp_gt_u32_e32 vcc, s59, v16
	s_cbranch_vccnz .LBB0_100

.LBB0_1750:
	s_sleep 2
	global_load_dword v0, v17, s[6:7] sc1
	s_waitcnt vmcnt(0)
	v_cmp_gt_u32_e32 vcc, s36, v0
	s_cbranch_vccnz .LBB0_1750
	s_getpc_b64 s[98:99]
